# SSD segment-state hand-off: sc1 (agent-coherent) loads of the write-through states and decays instead of buffer_inv after the flag poll
# speedup vs baseline: 1.0035x; 1.0035x over previous
.LBB0_443:
	s_waitcnt vmcnt(0)
	s_nop 0
	s_waitcnt vmcnt(0)
.LBB0_444:
	v_readlane_b32 s14, v253, 28
	s_add_i32 s14, s52, s14
	s_add_u32 s23, s6, 0x80000
	s_mul_i32 s14, s14, 7
	s_addc_u32 s30, s7, 0
	s_ashr_i32 s15, s14, 31
	s_lshl_b64 s[14:15], s[14:15], 14
	s_add_u32 s14, s4, s14
	s_addc_u32 s15, s5, s15
	s_lshl_b32 s16, s92, 12
	s_add_u32 s14, s14, s16
	s_waitcnt lgkmcnt(0)
	s_barrier
	s_addc_u32 s15, s15, 0
	v_lshl_add_u64 v[62:63], v[60:61], 3, s[14:15]
	global_load_dwordx2 v[112:113], v[62:63], off sc1
	global_load_dwordx2 v[110:111], v[62:63], off offset:512 sc1
	global_load_dwordx2 v[108:109], v[62:63], off offset:1024 sc1
	global_load_dwordx2 v[106:107], v[62:63], off offset:1536 sc1
	global_load_dwordx2 v[104:105], v[62:63], off offset:2048 sc1
	global_load_dwordx2 v[102:103], v[62:63], off offset:2560 sc1
	global_load_dwordx2 v[100:101], v[62:63], off offset:3072 sc1
	global_load_dwordx2 v[98:99], v[62:63], off offset:3584 sc1
	v_mov_b32_e32 v30, v3
	v_mov_b32_e32 v31, v3
	s_mul_i32 s14, s18, 7
	v_readlane_b32 s15, v254, 2
	v_mov_b32_e32 v28, v3
	v_mov_b32_e32 v29, v3
	v_mov_b64_e32 v[46:47], v[30:31]
	v_mov_b64_e32 v[50:51], v[30:31]
	v_mov_b64_e32 v[58:59], v[30:31]
	v_mov_b64_e32 v[34:35], v[30:31]
	v_mov_b64_e32 v[42:43], v[30:31]
	v_mov_b64_e32 v[38:39], v[30:31]
	v_mov_b64_e32 v[54:55], v[30:31]
	s_add_i32 s31, s15, s14
	s_mov_b32 s34, 2
	v_mov_b64_e32 v[44:45], v[28:29]
	v_mov_b64_e32 v[48:49], v[28:29]
	v_mov_b64_e32 v[56:57], v[28:29]
	v_mov_b64_e32 v[32:33], v[28:29]
	v_mov_b64_e32 v[40:41], v[28:29]
	v_mov_b64_e32 v[36:37], v[28:29]
	v_mov_b64_e32 v[52:53], v[28:29]
.LBB0_445:
	s_add_i32 s14, s34, -1
	s_cmp_lt_u32 s14, s35
	s_cselect_b64 s[16:17], -1, 0
	s_cmp_ge_u32 s14, s35
	s_cbranch_scc1 .LBB0_447
	v_add_co_u32_e32 v78, vcc, 0x4000, v62
	s_nop 1
	v_addc_co_u32_e32 v79, vcc, 0, v63, vcc
	global_load_dwordx2 v[74:75], v[78:79], off sc1
	global_load_dwordx2 v[72:73], v[78:79], off offset:512 sc1
	global_load_dwordx2 v[70:71], v[78:79], off offset:1024 sc1
	global_load_dwordx2 v[68:69], v[78:79], off offset:1536 sc1
	global_load_dwordx2 v[66:67], v[78:79], off offset:2048 sc1
	global_load_dwordx2 v[64:65], v[78:79], off offset:2560 sc1
	global_load_dwordx2 v[76:77], v[78:79], off offset:3072 sc1
	s_nop 0
	global_load_dwordx2 v[78:79], v[78:79], off offset:3584 sc1
.LBB0_447:
	s_add_i32 s14, s31, s34
	s_add_i32 s14, s14, -2
	s_ashr_i32 s15, s14, 31
	s_lshl_b64 s[14:15], s[14:15], 2
	s_add_u32 s28, s23, s14
	s_addc_u32 s29, s30, s15
	global_load_dword v61, v3, s[28:29] sc1
	s_cmp_ge_u32 s34, s35
	s_cselect_b64 s[14:15], -1, 0
	s_and_b64 vcc, exec, s[14:15]
	s_waitcnt vmcnt(8)
	v_mov_b64_e32 v[80:81], v[112:113]
	s_waitcnt vmcnt(7)
	v_mov_b64_e32 v[82:83], v[110:111]
	s_waitcnt vmcnt(6)
	v_mov_b64_e32 v[86:87], v[108:109]
	s_waitcnt vmcnt(5)
	v_mov_b64_e32 v[88:89], v[106:107]
	s_waitcnt vmcnt(4)
	v_mov_b64_e32 v[90:91], v[104:105]
	s_waitcnt vmcnt(3)
	v_mov_b64_e32 v[92:93], v[102:103]
	s_waitcnt vmcnt(2)
	v_mov_b64_e32 v[94:95], v[100:101]
	s_waitcnt vmcnt(1)
	v_mov_b64_e32 v[96:97], v[98:99]
	s_cbranch_vccnz .LBB0_449
	v_add_co_u32_e32 v96, vcc, 0x8000, v62
	s_nop 1
	v_addc_co_u32_e32 v97, vcc, 0, v63, vcc
	global_load_dwordx2 v[80:81], v[96:97], off sc1
	global_load_dwordx2 v[82:83], v[96:97], off offset:512 sc1
	global_load_dwordx2 v[86:87], v[96:97], off offset:1024 sc1
	global_load_dwordx2 v[88:89], v[96:97], off offset:1536 sc1
	global_load_dwordx2 v[90:91], v[96:97], off offset:2048 sc1
	global_load_dwordx2 v[92:93], v[96:97], off offset:2560 sc1
	global_load_dwordx2 v[94:95], v[96:97], off offset:3072 sc1
	s_nop 0
	global_load_dwordx2 v[96:97], v[96:97], off offset:3584 sc1
.LBB0_449:
	s_waitcnt vmcnt(0)
	v_mul_f32_e32 v61, 0x3fb8aa3b, v61
	v_exp_f32_e32 v120, v61
	v_lshlrev_b32_e32 v122, 16, v112
	v_and_b32_e32 v123, 0xffff0000, v112
	v_lshlrev_b32_e32 v112, 16, v113
	v_and_b32_e32 v113, 0xffff0000, v113
	v_pk_fma_f32 v[30:31], v[30:31], v[120:121], v[112:113] op_sel_hi:[1,0,1]
	v_lshlrev_b32_e32 v112, 16, v110
	v_and_b32_e32 v113, 0xffff0000, v110
	v_lshlrev_b32_e32 v110, 16, v111
	v_and_b32_e32 v111, 0xffff0000, v111
	v_pk_fma_f32 v[46:47], v[46:47], v[120:121], v[110:111] op_sel_hi:[1,0,1]
	v_lshlrev_b32_e32 v110, 16, v108
	v_and_b32_e32 v111, 0xffff0000, v108
	v_lshlrev_b32_e32 v108, 16, v109
	v_and_b32_e32 v109, 0xffff0000, v109
	v_pk_fma_f32 v[50:51], v[50:51], v[120:121], v[108:109] op_sel_hi:[1,0,1]
	v_lshlrev_b32_e32 v108, 16, v106
	v_and_b32_e32 v109, 0xffff0000, v106
	v_lshlrev_b32_e32 v106, 16, v107
	v_and_b32_e32 v107, 0xffff0000, v107
	v_pk_fma_f32 v[58:59], v[58:59], v[120:121], v[106:107] op_sel_hi:[1,0,1]
	v_lshlrev_b32_e32 v106, 16, v104
	v_and_b32_e32 v107, 0xffff0000, v104
	v_lshlrev_b32_e32 v104, 16, v105
	v_and_b32_e32 v105, 0xffff0000, v105
	v_pk_fma_f32 v[34:35], v[34:35], v[120:121], v[104:105] op_sel_hi:[1,0,1]
	v_lshlrev_b32_e32 v104, 16, v102
	v_and_b32_e32 v105, 0xffff0000, v102
	v_lshlrev_b32_e32 v102, 16, v103
	v_and_b32_e32 v103, 0xffff0000, v103
	v_pk_fma_f32 v[42:43], v[42:43], v[120:121], v[102:103] op_sel_hi:[1,0,1]
	v_lshlrev_b32_e32 v102, 16, v100
	v_and_b32_e32 v103, 0xffff0000, v100
	v_lshlrev_b32_e32 v100, 16, v101
	v_and_b32_e32 v101, 0xffff0000, v101
	v_pk_fma_f32 v[38:39], v[38:39], v[120:121], v[100:101] op_sel_hi:[1,0,1]
	v_lshlrev_b32_e32 v100, 16, v98
	v_and_b32_e32 v101, 0xffff0000, v98
	v_lshlrev_b32_e32 v98, 16, v99
	v_and_b32_e32 v99, 0xffff0000, v99
	v_pk_fma_f32 v[28:29], v[28:29], v[120:121], v[122:123] op_sel_hi:[1,0,1]
	v_pk_fma_f32 v[44:45], v[44:45], v[120:121], v[112:113] op_sel_hi:[1,0,1]
	v_pk_fma_f32 v[48:49], v[48:49], v[120:121], v[110:111] op_sel_hi:[1,0,1]
	v_pk_fma_f32 v[56:57], v[56:57], v[120:121], v[108:109] op_sel_hi:[1,0,1]
	v_pk_fma_f32 v[32:33], v[32:33], v[120:121], v[106:107] op_sel_hi:[1,0,1]
	v_pk_fma_f32 v[40:41], v[40:41], v[120:121], v[104:105] op_sel_hi:[1,0,1]
	v_pk_fma_f32 v[36:37], v[36:37], v[120:121], v[102:103] op_sel_hi:[1,0,1]
	v_pk_fma_f32 v[54:55], v[54:55], v[120:121], v[98:99] op_sel_hi:[1,0,1]
	s_andn2_b64 vcc, exec, s[16:17]
	v_pk_fma_f32 v[52:53], v[52:53], v[120:121], v[100:101] op_sel_hi:[1,0,1]
	s_cbranch_vccnz .LBB0_451
	global_load_dword v61, v3, s[28:29] offset:4 sc1
	v_lshlrev_b32_e32 v100, 16, v74
	v_and_b32_e32 v101, 0xffff0000, v74
	v_lshlrev_b32_e32 v102, 16, v75
	v_and_b32_e32 v103, 0xffff0000, v75
	s_waitcnt vmcnt(0)
	v_mul_f32_e32 v61, 0x3fb8aa3b, v61
	v_exp_f32_e32 v98, v61
	s_nop 0
	v_pk_fma_f32 v[30:31], v[30:31], v[98:99], v[102:103] op_sel_hi:[1,0,1]
	v_pk_fma_f32 v[28:29], v[28:29], v[98:99], v[100:101] op_sel_hi:[1,0,1]
	v_lshlrev_b32_e32 v100, 16, v72
	v_and_b32_e32 v101, 0xffff0000, v72
	v_lshlrev_b32_e32 v102, 16, v73
	v_and_b32_e32 v103, 0xffff0000, v73
	v_pk_fma_f32 v[46:47], v[46:47], v[98:99], v[102:103] op_sel_hi:[1,0,1]
	v_pk_fma_f32 v[44:45], v[44:45], v[98:99], v[100:101] op_sel_hi:[1,0,1]
	v_lshlrev_b32_e32 v100, 16, v70
	v_and_b32_e32 v101, 0xffff0000, v70
	v_lshlrev_b32_e32 v102, 16, v71
	v_and_b32_e32 v103, 0xffff0000, v71
	v_pk_fma_f32 v[50:51], v[50:51], v[98:99], v[102:103] op_sel_hi:[1,0,1]
	v_pk_fma_f32 v[48:49], v[48:49], v[98:99], v[100:101] op_sel_hi:[1,0,1]
	v_lshlrev_b32_e32 v100, 16, v68
	v_and_b32_e32 v101, 0xffff0000, v68
	v_lshlrev_b32_e32 v102, 16, v69
	v_and_b32_e32 v103, 0xffff0000, v69
	v_pk_fma_f32 v[58:59], v[58:59], v[98:99], v[102:103] op_sel_hi:[1,0,1]
	v_pk_fma_f32 v[56:57], v[56:57], v[98:99], v[100:101] op_sel_hi:[1,0,1]
	v_lshlrev_b32_e32 v100, 16, v66
	v_and_b32_e32 v101, 0xffff0000, v66
	v_lshlrev_b32_e32 v102, 16, v67
	v_and_b32_e32 v103, 0xffff0000, v67
	v_pk_fma_f32 v[34:35], v[34:35], v[98:99], v[102:103] op_sel_hi:[1,0,1]
	v_pk_fma_f32 v[32:33], v[32:33], v[98:99], v[100:101] op_sel_hi:[1,0,1]
	v_lshlrev_b32_e32 v100, 16, v64
	v_and_b32_e32 v101, 0xffff0000, v64
	v_lshlrev_b32_e32 v102, 16, v65
	v_and_b32_e32 v103, 0xffff0000, v65
	v_pk_fma_f32 v[42:43], v[42:43], v[98:99], v[102:103] op_sel_hi:[1,0,1]
	v_pk_fma_f32 v[40:41], v[40:41], v[98:99], v[100:101] op_sel_hi:[1,0,1]
	v_lshlrev_b32_e32 v100, 16, v76
	v_and_b32_e32 v101, 0xffff0000, v76
	v_lshlrev_b32_e32 v102, 16, v77
	v_and_b32_e32 v103, 0xffff0000, v77
	v_pk_fma_f32 v[38:39], v[38:39], v[98:99], v[102:103] op_sel_hi:[1,0,1]
	v_pk_fma_f32 v[36:37], v[36:37], v[98:99], v[100:101] op_sel_hi:[1,0,1]
	v_lshlrev_b32_e32 v100, 16, v78
	v_and_b32_e32 v101, 0xffff0000, v78
	v_lshlrev_b32_e32 v102, 16, v79
	v_and_b32_e32 v103, 0xffff0000, v79
	v_pk_fma_f32 v[54:55], v[54:55], v[98:99], v[102:103] op_sel_hi:[1,0,1]
	v_pk_fma_f32 v[52:53], v[52:53], v[98:99], v[100:101] op_sel_hi:[1,0,1]
